# P11 sample-row small GEMM K loop rescheduled: straight-line, 32 fragment loads always in flight
# baseline (speedup 1.0000x reference)
; template <class Epi, bool PAIR>
; __device__ __forceinline__ void small_gemm(LAS unsigned char* lds, const bf16_t* A, int lda, const bf16_t* B, int ldb, int K, int nrg, int nct, size_t row_base, int col_base, const Epi& E, int G, int c) {
;     ...
;         const bf16_t* ap = A + (size_t)(rg * 64 + fr) * lda + k0 + fq * 8;
;         const bf16_t* bp;
;         if (PAIR) { const int ch0 = 32 * ct; bp = B + (size_t)(DSSM + 256 * (ch0 >> 7) + (ch0 & 127) + fr) * ldb + k0 + fq * 8; }
;         else bp = B + (size_t)(ct * 64 + fr) * ldb + k0 + fq * 8;
; #pragma unroll 4
;         for (int ks = 0; ks < nks; ++ks) {
;             bf16x8 a[4], b[4];
; #pragma unroll
;             for (int mi = 0; mi < 4; ++mi) a[mi] = *(const bf16x8*)(ap + (size_t)(mi * 16) * lda + ks * 32);
; #pragma unroll
;             for (int ni = 0; ni < 4; ++ni) { const int roff = PAIR ? ((ni & 1) * 16 + (ni >> 1) * 128) : ni * 16; b[ni] = *(const bf16x8*)(bp + (size_t)roff * ldb + ks * 32); }
; #pragma unroll
;             for (int mi = 0; mi < 4; ++mi)
; #pragma unroll
;                 for (int ni = 0; ni < 4; ++ni) acc[mi][ni] = __builtin_amdgcn_mfma_f32_16x16x32_bf16(b[ni], a[mi], acc[mi][ni], 0, 0, 0);
;         }
.LBB0_1487:
	v_add_co_u32_e32 v136, vcc, s1, v68
	s_nop 1
	v_addc_co_u32_e32 v137, vcc, 0, v69, vcc
	v_add_co_u32_e32 v138, vcc, s3, v68
	s_nop 1
	v_addc_co_u32_e32 v139, vcc, 0, v69, vcc
	v_add_co_u32_e32 v148, vcc, s5, v68
	s_nop 1
	v_addc_co_u32_e32 v149, vcc, 0, v69, vcc
	v_add_co_u32_e32 v150, vcc, s8, v68
	s_nop 1
	v_addc_co_u32_e32 v151, vcc, 0, v69, vcc
	v_add_co_u32_e32 v140, vcc, s9, v70
	s_nop 1
	v_addc_co_u32_e32 v141, vcc, 0, v71, vcc
	v_add_co_u32_e32 v142, vcc, s10, v70
	s_nop 1
	v_addc_co_u32_e32 v143, vcc, 0, v71, vcc
	v_add_co_u32_e32 v144, vcc, s11, v70
	s_nop 1
	v_addc_co_u32_e32 v145, vcc, 0, v71, vcc
	v_add_co_u32_e32 v146, vcc, s12, v70
	s_nop 1
	v_addc_co_u32_e32 v147, vcc, 0, v71, vcc
	global_load_dwordx4 v[84:87], v[136:137], off
	global_load_dwordx4 v[88:91], v[138:139], off
	global_load_dwordx4 v[92:95], v[148:149], off
	global_load_dwordx4 v[96:99], v[150:151], off
	global_load_dwordx4 v[100:103], v[140:141], off
	global_load_dwordx4 v[104:107], v[142:143], off
	global_load_dwordx4 v[108:111], v[144:145], off
	global_load_dwordx4 v[112:115], v[146:147], off
	global_load_dwordx4 v[116:119], v[136:137], off offset:64
	global_load_dwordx4 v[120:123], v[138:139], off offset:64
	global_load_dwordx4 v[124:127], v[148:149], off offset:64
	global_load_dwordx4 v[128:131], v[150:151], off offset:64
	global_load_dwordx4 v[132:135], v[140:141], off offset:64
	global_load_dwordx4 v[152:155], v[142:143], off offset:64
	global_load_dwordx4 v[156:159], v[144:145], off offset:64
	global_load_dwordx4 v[160:163], v[146:147], off offset:64
	global_load_dwordx4 v[164:167], v[136:137], off offset:128
	global_load_dwordx4 v[168:171], v[138:139], off offset:128
	global_load_dwordx4 v[172:175], v[148:149], off offset:128
	global_load_dwordx4 v[176:179], v[150:151], off offset:128
	global_load_dwordx4 v[180:183], v[140:141], off offset:128
	global_load_dwordx4 v[184:187], v[142:143], off offset:128
	global_load_dwordx4 v[188:191], v[144:145], off offset:128
	global_load_dwordx4 v[192:195], v[146:147], off offset:128
	global_load_dwordx4 v[196:199], v[136:137], off offset:192
	global_load_dwordx4 v[204:207], v[138:139], off offset:192
	global_load_dwordx4 v[208:211], v[148:149], off offset:192
	global_load_dwordx4 v[212:215], v[150:151], off offset:192
	global_load_dwordx4 v[216:219], v[140:141], off offset:192
	global_load_dwordx4 v[220:223], v[142:143], off offset:192
	global_load_dwordx4 v[224:227], v[144:145], off offset:192
	global_load_dwordx4 v[228:231], v[146:147], off offset:192
	s_waitcnt vmcnt(24)
	v_mfma_f32_16x16x32_bf16 v[56:59], v[100:103], v[84:87], v[56:59]
	v_mfma_f32_16x16x32_bf16 v[44:47], v[104:107], v[84:87], v[44:47]
	v_mfma_f32_16x16x32_bf16 v[24:27], v[108:111], v[84:87], v[24:27]
	v_mfma_f32_16x16x32_bf16 v[16:19], v[112:115], v[84:87], v[16:19]
	v_mfma_f32_16x16x32_bf16 v[12:15], v[100:103], v[88:91], v[12:15]
	v_mfma_f32_16x16x32_bf16 v[8:11], v[104:107], v[88:91], v[8:11]
	v_mfma_f32_16x16x32_bf16 v[4:7], v[108:111], v[88:91], v[4:7]
	v_mfma_f32_16x16x32_bf16 v[0:3], v[112:115], v[88:91], v[0:3]
	v_mfma_f32_16x16x32_bf16 v[20:23], v[100:103], v[92:95], v[20:23]
	v_mfma_f32_16x16x32_bf16 v[28:31], v[104:107], v[92:95], v[28:31]
	v_mfma_f32_16x16x32_bf16 v[32:35], v[108:111], v[92:95], v[32:35]
	v_mfma_f32_16x16x32_bf16 v[36:39], v[112:115], v[92:95], v[36:39]
	v_mfma_f32_16x16x32_bf16 v[40:43], v[100:103], v[96:99], v[40:43]
	v_mfma_f32_16x16x32_bf16 v[48:51], v[104:107], v[96:99], v[48:51]
	v_mfma_f32_16x16x32_bf16 v[52:55], v[108:111], v[96:99], v[52:55]
	v_mfma_f32_16x16x32_bf16 v[60:63], v[112:115], v[96:99], v[60:63]
	global_load_dwordx4 v[84:87], v[136:137], off offset:256
	global_load_dwordx4 v[88:91], v[138:139], off offset:256
	global_load_dwordx4 v[92:95], v[148:149], off offset:256
	global_load_dwordx4 v[96:99], v[150:151], off offset:256
	global_load_dwordx4 v[100:103], v[140:141], off offset:256
	global_load_dwordx4 v[104:107], v[142:143], off offset:256
	global_load_dwordx4 v[108:111], v[144:145], off offset:256
	global_load_dwordx4 v[112:115], v[146:147], off offset:256
	s_waitcnt vmcnt(24)
	v_mfma_f32_16x16x32_bf16 v[56:59], v[132:135], v[116:119], v[56:59]
	v_mfma_f32_16x16x32_bf16 v[44:47], v[152:155], v[116:119], v[44:47]
	v_mfma_f32_16x16x32_bf16 v[24:27], v[156:159], v[116:119], v[24:27]
	v_mfma_f32_16x16x32_bf16 v[16:19], v[160:163], v[116:119], v[16:19]
	v_mfma_f32_16x16x32_bf16 v[12:15], v[132:135], v[120:123], v[12:15]
	v_mfma_f32_16x16x32_bf16 v[8:11], v[152:155], v[120:123], v[8:11]
	v_mfma_f32_16x16x32_bf16 v[4:7], v[156:159], v[120:123], v[4:7]
	v_mfma_f32_16x16x32_bf16 v[0:3], v[160:163], v[120:123], v[0:3]
	v_mfma_f32_16x16x32_bf16 v[20:23], v[132:135], v[124:127], v[20:23]
	v_mfma_f32_16x16x32_bf16 v[28:31], v[152:155], v[124:127], v[28:31]
	v_mfma_f32_16x16x32_bf16 v[32:35], v[156:159], v[124:127], v[32:35]
	v_mfma_f32_16x16x32_bf16 v[36:39], v[160:163], v[124:127], v[36:39]
	v_mfma_f32_16x16x32_bf16 v[40:43], v[132:135], v[128:131], v[40:43]
	v_mfma_f32_16x16x32_bf16 v[48:51], v[152:155], v[128:131], v[48:51]
	v_mfma_f32_16x16x32_bf16 v[52:55], v[156:159], v[128:131], v[52:55]
	v_mfma_f32_16x16x32_bf16 v[60:63], v[160:163], v[128:131], v[60:63]
	global_load_dwordx4 v[116:119], v[136:137], off offset:320
	global_load_dwordx4 v[120:123], v[138:139], off offset:320
	global_load_dwordx4 v[124:127], v[148:149], off offset:320
	global_load_dwordx4 v[128:131], v[150:151], off offset:320
	global_load_dwordx4 v[132:135], v[140:141], off offset:320
	global_load_dwordx4 v[152:155], v[142:143], off offset:320
	global_load_dwordx4 v[156:159], v[144:145], off offset:320
	global_load_dwordx4 v[160:163], v[146:147], off offset:320
	s_waitcnt vmcnt(24)
; template <class Epi, bool PAIR>
; __device__ __forceinline__ void small_gemm(LAS unsigned char* lds, const bf16_t* A, int lda, const bf16_t* B, int ldb, int K, int nrg, int nct, size_t row_base, int col_base, const Epi& E, int G, int c) {
;     ...
;         for (int ks = 0; ks < nks; ++ks) {
;             bf16x8 a[4], b[4];
; #pragma unroll
;             for (int mi = 0; mi < 4; ++mi) a[mi] = *(const bf16x8*)(ap + (size_t)(mi * 16) * lda + ks * 32);
; #pragma unroll
;             for (int ni = 0; ni < 4; ++ni) { const int roff = PAIR ? ((ni & 1) * 16 + (ni >> 1) * 128) : ni * 16; b[ni] = *(const bf16x8*)(bp + (size_t)roff * ldb + ks * 32); }
; #pragma unroll
;             for (int mi = 0; mi < 4; ++mi)
; #pragma unroll
;                 for (int ni = 0; ni < 4; ++ni) acc[mi][ni] = __builtin_amdgcn_mfma_f32_16x16x32_bf16(b[ni], a[mi], acc[mi][ni], 0, 0, 0);
;         }
	v_mfma_f32_16x16x32_bf16 v[56:59], v[180:183], v[164:167], v[56:59]
	v_mfma_f32_16x16x32_bf16 v[44:47], v[184:187], v[164:167], v[44:47]
	v_mfma_f32_16x16x32_bf16 v[24:27], v[188:191], v[164:167], v[24:27]
	v_mfma_f32_16x16x32_bf16 v[16:19], v[192:195], v[164:167], v[16:19]
	v_mfma_f32_16x16x32_bf16 v[12:15], v[180:183], v[168:171], v[12:15]
	v_mfma_f32_16x16x32_bf16 v[8:11], v[184:187], v[168:171], v[8:11]
	v_mfma_f32_16x16x32_bf16 v[4:7], v[188:191], v[168:171], v[4:7]
	v_mfma_f32_16x16x32_bf16 v[0:3], v[192:195], v[168:171], v[0:3]
	v_mfma_f32_16x16x32_bf16 v[20:23], v[180:183], v[172:175], v[20:23]
	v_mfma_f32_16x16x32_bf16 v[28:31], v[184:187], v[172:175], v[28:31]
	v_mfma_f32_16x16x32_bf16 v[32:35], v[188:191], v[172:175], v[32:35]
	v_mfma_f32_16x16x32_bf16 v[36:39], v[192:195], v[172:175], v[36:39]
	v_mfma_f32_16x16x32_bf16 v[40:43], v[180:183], v[176:179], v[40:43]
	v_mfma_f32_16x16x32_bf16 v[48:51], v[184:187], v[176:179], v[48:51]
	v_mfma_f32_16x16x32_bf16 v[52:55], v[188:191], v[176:179], v[52:55]
	v_mfma_f32_16x16x32_bf16 v[60:63], v[192:195], v[176:179], v[60:63]
	global_load_dwordx4 v[164:167], v[136:137], off offset:384
	global_load_dwordx4 v[168:171], v[138:139], off offset:384
	global_load_dwordx4 v[172:175], v[148:149], off offset:384
	global_load_dwordx4 v[176:179], v[150:151], off offset:384
	global_load_dwordx4 v[180:183], v[140:141], off offset:384
	global_load_dwordx4 v[184:187], v[142:143], off offset:384
	global_load_dwordx4 v[188:191], v[144:145], off offset:384
	global_load_dwordx4 v[192:195], v[146:147], off offset:384
	s_waitcnt vmcnt(24)
	v_mfma_f32_16x16x32_bf16 v[56:59], v[216:219], v[196:199], v[56:59]
	v_mfma_f32_16x16x32_bf16 v[44:47], v[220:223], v[196:199], v[44:47]
	v_mfma_f32_16x16x32_bf16 v[24:27], v[224:227], v[196:199], v[24:27]
	v_mfma_f32_16x16x32_bf16 v[16:19], v[228:231], v[196:199], v[16:19]
	v_mfma_f32_16x16x32_bf16 v[12:15], v[216:219], v[204:207], v[12:15]
	v_mfma_f32_16x16x32_bf16 v[8:11], v[220:223], v[204:207], v[8:11]
	v_mfma_f32_16x16x32_bf16 v[4:7], v[224:227], v[204:207], v[4:7]
	v_mfma_f32_16x16x32_bf16 v[0:3], v[228:231], v[204:207], v[0:3]
	v_mfma_f32_16x16x32_bf16 v[20:23], v[216:219], v[208:211], v[20:23]
	v_mfma_f32_16x16x32_bf16 v[28:31], v[220:223], v[208:211], v[28:31]
	v_mfma_f32_16x16x32_bf16 v[32:35], v[224:227], v[208:211], v[32:35]
	v_mfma_f32_16x16x32_bf16 v[36:39], v[228:231], v[208:211], v[36:39]
	v_mfma_f32_16x16x32_bf16 v[40:43], v[216:219], v[212:215], v[40:43]
	v_mfma_f32_16x16x32_bf16 v[48:51], v[220:223], v[212:215], v[48:51]
	v_mfma_f32_16x16x32_bf16 v[52:55], v[224:227], v[212:215], v[52:55]
	v_mfma_f32_16x16x32_bf16 v[60:63], v[228:231], v[212:215], v[60:63]
	global_load_dwordx4 v[196:199], v[136:137], off offset:448
	global_load_dwordx4 v[204:207], v[138:139], off offset:448
	global_load_dwordx4 v[208:211], v[148:149], off offset:448
	global_load_dwordx4 v[212:215], v[150:151], off offset:448
	global_load_dwordx4 v[216:219], v[140:141], off offset:448
	global_load_dwordx4 v[220:223], v[142:143], off offset:448
	global_load_dwordx4 v[224:227], v[144:145], off offset:448
	global_load_dwordx4 v[228:231], v[146:147], off offset:448
	s_waitcnt vmcnt(24)
	v_mfma_f32_16x16x32_bf16 v[56:59], v[100:103], v[84:87], v[56:59]
	v_mfma_f32_16x16x32_bf16 v[44:47], v[104:107], v[84:87], v[44:47]
	v_mfma_f32_16x16x32_bf16 v[24:27], v[108:111], v[84:87], v[24:27]
	v_mfma_f32_16x16x32_bf16 v[16:19], v[112:115], v[84:87], v[16:19]
	v_mfma_f32_16x16x32_bf16 v[12:15], v[100:103], v[88:91], v[12:15]
	v_mfma_f32_16x16x32_bf16 v[8:11], v[104:107], v[88:91], v[8:11]
	v_mfma_f32_16x16x32_bf16 v[4:7], v[108:111], v[88:91], v[4:7]
	v_mfma_f32_16x16x32_bf16 v[0:3], v[112:115], v[88:91], v[0:3]
	v_mfma_f32_16x16x32_bf16 v[20:23], v[100:103], v[92:95], v[20:23]
	v_mfma_f32_16x16x32_bf16 v[28:31], v[104:107], v[92:95], v[28:31]
	v_mfma_f32_16x16x32_bf16 v[32:35], v[108:111], v[92:95], v[32:35]
	v_mfma_f32_16x16x32_bf16 v[36:39], v[112:115], v[92:95], v[36:39]
	v_mfma_f32_16x16x32_bf16 v[40:43], v[100:103], v[96:99], v[40:43]
	v_mfma_f32_16x16x32_bf16 v[48:51], v[104:107], v[96:99], v[48:51]
	v_mfma_f32_16x16x32_bf16 v[52:55], v[108:111], v[96:99], v[52:55]
	v_mfma_f32_16x16x32_bf16 v[60:63], v[112:115], v[96:99], v[60:63]
	global_load_dwordx4 v[84:87], v[136:137], off offset:512
	global_load_dwordx4 v[88:91], v[138:139], off offset:512
	global_load_dwordx4 v[92:95], v[148:149], off offset:512
	global_load_dwordx4 v[96:99], v[150:151], off offset:512
	global_load_dwordx4 v[100:103], v[140:141], off offset:512
	global_load_dwordx4 v[104:107], v[142:143], off offset:512
	global_load_dwordx4 v[108:111], v[144:145], off offset:512
	global_load_dwordx4 v[112:115], v[146:147], off offset:512
	s_waitcnt vmcnt(24)
	v_mfma_f32_16x16x32_bf16 v[56:59], v[132:135], v[116:119], v[56:59]
	v_mfma_f32_16x16x32_bf16 v[44:47], v[152:155], v[116:119], v[44:47]
	v_mfma_f32_16x16x32_bf16 v[24:27], v[156:159], v[116:119], v[24:27]
	v_mfma_f32_16x16x32_bf16 v[16:19], v[160:163], v[116:119], v[16:19]
	v_mfma_f32_16x16x32_bf16 v[12:15], v[132:135], v[120:123], v[12:15]
	v_mfma_f32_16x16x32_bf16 v[8:11], v[152:155], v[120:123], v[8:11]
	v_mfma_f32_16x16x32_bf16 v[4:7], v[156:159], v[120:123], v[4:7]
	v_mfma_f32_16x16x32_bf16 v[0:3], v[160:163], v[120:123], v[0:3]
	v_mfma_f32_16x16x32_bf16 v[20:23], v[132:135], v[124:127], v[20:23]
	v_mfma_f32_16x16x32_bf16 v[28:31], v[152:155], v[124:127], v[28:31]
	v_mfma_f32_16x16x32_bf16 v[32:35], v[156:159], v[124:127], v[32:35]
	v_mfma_f32_16x16x32_bf16 v[36:39], v[160:163], v[124:127], v[36:39]
	v_mfma_f32_16x16x32_bf16 v[40:43], v[132:135], v[128:131], v[40:43]
	v_mfma_f32_16x16x32_bf16 v[48:51], v[152:155], v[128:131], v[48:51]
	v_mfma_f32_16x16x32_bf16 v[52:55], v[156:159], v[128:131], v[52:55]
	v_mfma_f32_16x16x32_bf16 v[60:63], v[160:163], v[128:131], v[60:63]
	global_load_dwordx4 v[116:119], v[136:137], off offset:576
	global_load_dwordx4 v[120:123], v[138:139], off offset:576
	global_load_dwordx4 v[124:127], v[148:149], off offset:576
	global_load_dwordx4 v[128:131], v[150:151], off offset:576
	global_load_dwordx4 v[132:135], v[140:141], off offset:576
	global_load_dwordx4 v[152:155], v[142:143], off offset:576
	global_load_dwordx4 v[156:159], v[144:145], off offset:576
	global_load_dwordx4 v[160:163], v[146:147], off offset:576
	s_waitcnt vmcnt(24)
; template <class Epi, bool PAIR>
; __device__ __forceinline__ void small_gemm(LAS unsigned char* lds, const bf16_t* A, int lda, const bf16_t* B, int ldb, int K, int nrg, int nct, size_t row_base, int col_base, const Epi& E, int G, int c) {
;     ...
;         for (int ks = 0; ks < nks; ++ks) {
;             bf16x8 a[4], b[4];
; #pragma unroll
;             for (int mi = 0; mi < 4; ++mi) a[mi] = *(const bf16x8*)(ap + (size_t)(mi * 16) * lda + ks * 32);
; #pragma unroll
;             for (int ni = 0; ni < 4; ++ni) { const int roff = PAIR ? ((ni & 1) * 16 + (ni >> 1) * 128) : ni * 16; b[ni] = *(const bf16x8*)(bp + (size_t)roff * ldb + ks * 32); }
; #pragma unroll
;             for (int mi = 0; mi < 4; ++mi)
; #pragma unroll
;                 for (int ni = 0; ni < 4; ++ni) acc[mi][ni] = __builtin_amdgcn_mfma_f32_16x16x32_bf16(b[ni], a[mi], acc[mi][ni], 0, 0, 0);
;         }
	v_mfma_f32_16x16x32_bf16 v[56:59], v[180:183], v[164:167], v[56:59]
	v_mfma_f32_16x16x32_bf16 v[44:47], v[184:187], v[164:167], v[44:47]
	v_mfma_f32_16x16x32_bf16 v[24:27], v[188:191], v[164:167], v[24:27]
	v_mfma_f32_16x16x32_bf16 v[16:19], v[192:195], v[164:167], v[16:19]
	v_mfma_f32_16x16x32_bf16 v[12:15], v[180:183], v[168:171], v[12:15]
	v_mfma_f32_16x16x32_bf16 v[8:11], v[184:187], v[168:171], v[8:11]
	v_mfma_f32_16x16x32_bf16 v[4:7], v[188:191], v[168:171], v[4:7]
	v_mfma_f32_16x16x32_bf16 v[0:3], v[192:195], v[168:171], v[0:3]
	v_mfma_f32_16x16x32_bf16 v[20:23], v[180:183], v[172:175], v[20:23]
	v_mfma_f32_16x16x32_bf16 v[28:31], v[184:187], v[172:175], v[28:31]
	v_mfma_f32_16x16x32_bf16 v[32:35], v[188:191], v[172:175], v[32:35]
	v_mfma_f32_16x16x32_bf16 v[36:39], v[192:195], v[172:175], v[36:39]
	v_mfma_f32_16x16x32_bf16 v[40:43], v[180:183], v[176:179], v[40:43]
	v_mfma_f32_16x16x32_bf16 v[48:51], v[184:187], v[176:179], v[48:51]
	v_mfma_f32_16x16x32_bf16 v[52:55], v[188:191], v[176:179], v[52:55]
	v_mfma_f32_16x16x32_bf16 v[60:63], v[192:195], v[176:179], v[60:63]
	global_load_dwordx4 v[164:167], v[136:137], off offset:640
	global_load_dwordx4 v[168:171], v[138:139], off offset:640
	global_load_dwordx4 v[172:175], v[148:149], off offset:640
	global_load_dwordx4 v[176:179], v[150:151], off offset:640
	global_load_dwordx4 v[180:183], v[140:141], off offset:640
	global_load_dwordx4 v[184:187], v[142:143], off offset:640
	global_load_dwordx4 v[188:191], v[144:145], off offset:640
	global_load_dwordx4 v[192:195], v[146:147], off offset:640
	s_waitcnt vmcnt(24)
	v_mfma_f32_16x16x32_bf16 v[56:59], v[216:219], v[196:199], v[56:59]
	v_mfma_f32_16x16x32_bf16 v[44:47], v[220:223], v[196:199], v[44:47]
	v_mfma_f32_16x16x32_bf16 v[24:27], v[224:227], v[196:199], v[24:27]
	v_mfma_f32_16x16x32_bf16 v[16:19], v[228:231], v[196:199], v[16:19]
	v_mfma_f32_16x16x32_bf16 v[12:15], v[216:219], v[204:207], v[12:15]
	v_mfma_f32_16x16x32_bf16 v[8:11], v[220:223], v[204:207], v[8:11]
	v_mfma_f32_16x16x32_bf16 v[4:7], v[224:227], v[204:207], v[4:7]
	v_mfma_f32_16x16x32_bf16 v[0:3], v[228:231], v[204:207], v[0:3]
	v_mfma_f32_16x16x32_bf16 v[20:23], v[216:219], v[208:211], v[20:23]
	v_mfma_f32_16x16x32_bf16 v[28:31], v[220:223], v[208:211], v[28:31]
	v_mfma_f32_16x16x32_bf16 v[32:35], v[224:227], v[208:211], v[32:35]
	v_mfma_f32_16x16x32_bf16 v[36:39], v[228:231], v[208:211], v[36:39]
	v_mfma_f32_16x16x32_bf16 v[40:43], v[216:219], v[212:215], v[40:43]
	v_mfma_f32_16x16x32_bf16 v[48:51], v[220:223], v[212:215], v[48:51]
	v_mfma_f32_16x16x32_bf16 v[52:55], v[224:227], v[212:215], v[52:55]
	v_mfma_f32_16x16x32_bf16 v[60:63], v[228:231], v[212:215], v[60:63]
	global_load_dwordx4 v[196:199], v[136:137], off offset:704
	global_load_dwordx4 v[204:207], v[138:139], off offset:704
	global_load_dwordx4 v[208:211], v[148:149], off offset:704
	global_load_dwordx4 v[212:215], v[150:151], off offset:704
	global_load_dwordx4 v[216:219], v[140:141], off offset:704
	global_load_dwordx4 v[220:223], v[142:143], off offset:704
	global_load_dwordx4 v[224:227], v[144:145], off offset:704
	global_load_dwordx4 v[228:231], v[146:147], off offset:704
	s_waitcnt vmcnt(24)
	v_mfma_f32_16x16x32_bf16 v[56:59], v[100:103], v[84:87], v[56:59]
	v_mfma_f32_16x16x32_bf16 v[44:47], v[104:107], v[84:87], v[44:47]
	v_mfma_f32_16x16x32_bf16 v[24:27], v[108:111], v[84:87], v[24:27]
	v_mfma_f32_16x16x32_bf16 v[16:19], v[112:115], v[84:87], v[16:19]
	v_mfma_f32_16x16x32_bf16 v[12:15], v[100:103], v[88:91], v[12:15]
	v_mfma_f32_16x16x32_bf16 v[8:11], v[104:107], v[88:91], v[8:11]
	v_mfma_f32_16x16x32_bf16 v[4:7], v[108:111], v[88:91], v[4:7]
	v_mfma_f32_16x16x32_bf16 v[0:3], v[112:115], v[88:91], v[0:3]
	v_mfma_f32_16x16x32_bf16 v[20:23], v[100:103], v[92:95], v[20:23]
	v_mfma_f32_16x16x32_bf16 v[28:31], v[104:107], v[92:95], v[28:31]
	v_mfma_f32_16x16x32_bf16 v[32:35], v[108:111], v[92:95], v[32:35]
	v_mfma_f32_16x16x32_bf16 v[36:39], v[112:115], v[92:95], v[36:39]
	v_mfma_f32_16x16x32_bf16 v[40:43], v[100:103], v[96:99], v[40:43]
	v_mfma_f32_16x16x32_bf16 v[48:51], v[104:107], v[96:99], v[48:51]
	v_mfma_f32_16x16x32_bf16 v[52:55], v[108:111], v[96:99], v[52:55]
	v_mfma_f32_16x16x32_bf16 v[60:63], v[112:115], v[96:99], v[60:63]
	global_load_dwordx4 v[84:87], v[136:137], off offset:768
	global_load_dwordx4 v[88:91], v[138:139], off offset:768
	global_load_dwordx4 v[92:95], v[148:149], off offset:768
	global_load_dwordx4 v[96:99], v[150:151], off offset:768
	global_load_dwordx4 v[100:103], v[140:141], off offset:768
	global_load_dwordx4 v[104:107], v[142:143], off offset:768
	global_load_dwordx4 v[108:111], v[144:145], off offset:768
	global_load_dwordx4 v[112:115], v[146:147], off offset:768
	s_waitcnt vmcnt(24)
	v_mfma_f32_16x16x32_bf16 v[56:59], v[132:135], v[116:119], v[56:59]
	v_mfma_f32_16x16x32_bf16 v[44:47], v[152:155], v[116:119], v[44:47]
	v_mfma_f32_16x16x32_bf16 v[24:27], v[156:159], v[116:119], v[24:27]
	v_mfma_f32_16x16x32_bf16 v[16:19], v[160:163], v[116:119], v[16:19]
	v_mfma_f32_16x16x32_bf16 v[12:15], v[132:135], v[120:123], v[12:15]
	v_mfma_f32_16x16x32_bf16 v[8:11], v[152:155], v[120:123], v[8:11]
	v_mfma_f32_16x16x32_bf16 v[4:7], v[156:159], v[120:123], v[4:7]
	v_mfma_f32_16x16x32_bf16 v[0:3], v[160:163], v[120:123], v[0:3]
	v_mfma_f32_16x16x32_bf16 v[20:23], v[132:135], v[124:127], v[20:23]
	v_mfma_f32_16x16x32_bf16 v[28:31], v[152:155], v[124:127], v[28:31]
	v_mfma_f32_16x16x32_bf16 v[32:35], v[156:159], v[124:127], v[32:35]
	v_mfma_f32_16x16x32_bf16 v[36:39], v[160:163], v[124:127], v[36:39]
	v_mfma_f32_16x16x32_bf16 v[40:43], v[132:135], v[128:131], v[40:43]
	v_mfma_f32_16x16x32_bf16 v[48:51], v[152:155], v[128:131], v[48:51]
	v_mfma_f32_16x16x32_bf16 v[52:55], v[156:159], v[128:131], v[52:55]
	v_mfma_f32_16x16x32_bf16 v[60:63], v[160:163], v[128:131], v[60:63]
	global_load_dwordx4 v[116:119], v[136:137], off offset:832
	global_load_dwordx4 v[120:123], v[138:139], off offset:832
	global_load_dwordx4 v[124:127], v[148:149], off offset:832
	global_load_dwordx4 v[128:131], v[150:151], off offset:832
	global_load_dwordx4 v[132:135], v[140:141], off offset:832
	global_load_dwordx4 v[152:155], v[142:143], off offset:832
	global_load_dwordx4 v[156:159], v[144:145], off offset:832
	global_load_dwordx4 v[160:163], v[146:147], off offset:832
	s_waitcnt vmcnt(24)
; template <class Epi, bool PAIR>
; __device__ __forceinline__ void small_gemm(LAS unsigned char* lds, const bf16_t* A, int lda, const bf16_t* B, int ldb, int K, int nrg, int nct, size_t row_base, int col_base, const Epi& E, int G, int c) {
;     ...
;         for (int ks = 0; ks < nks; ++ks) {
;             bf16x8 a[4], b[4];
; #pragma unroll
;             for (int mi = 0; mi < 4; ++mi) a[mi] = *(const bf16x8*)(ap + (size_t)(mi * 16) * lda + ks * 32);
; #pragma unroll
;             for (int ni = 0; ni < 4; ++ni) { const int roff = PAIR ? ((ni & 1) * 16 + (ni >> 1) * 128) : ni * 16; b[ni] = *(const bf16x8*)(bp + (size_t)roff * ldb + ks * 32); }
; #pragma unroll
;             for (int mi = 0; mi < 4; ++mi)
; #pragma unroll
;                 for (int ni = 0; ni < 4; ++ni) acc[mi][ni] = __builtin_amdgcn_mfma_f32_16x16x32_bf16(b[ni], a[mi], acc[mi][ni], 0, 0, 0);
;         }
	v_mfma_f32_16x16x32_bf16 v[56:59], v[180:183], v[164:167], v[56:59]
	v_mfma_f32_16x16x32_bf16 v[44:47], v[184:187], v[164:167], v[44:47]
	v_mfma_f32_16x16x32_bf16 v[24:27], v[188:191], v[164:167], v[24:27]
	v_mfma_f32_16x16x32_bf16 v[16:19], v[192:195], v[164:167], v[16:19]
	v_mfma_f32_16x16x32_bf16 v[12:15], v[180:183], v[168:171], v[12:15]
	v_mfma_f32_16x16x32_bf16 v[8:11], v[184:187], v[168:171], v[8:11]
	v_mfma_f32_16x16x32_bf16 v[4:7], v[188:191], v[168:171], v[4:7]
	v_mfma_f32_16x16x32_bf16 v[0:3], v[192:195], v[168:171], v[0:3]
	v_mfma_f32_16x16x32_bf16 v[20:23], v[180:183], v[172:175], v[20:23]
	v_mfma_f32_16x16x32_bf16 v[28:31], v[184:187], v[172:175], v[28:31]
	v_mfma_f32_16x16x32_bf16 v[32:35], v[188:191], v[172:175], v[32:35]
	v_mfma_f32_16x16x32_bf16 v[36:39], v[192:195], v[172:175], v[36:39]
	v_mfma_f32_16x16x32_bf16 v[40:43], v[180:183], v[176:179], v[40:43]
	v_mfma_f32_16x16x32_bf16 v[48:51], v[184:187], v[176:179], v[48:51]
	v_mfma_f32_16x16x32_bf16 v[52:55], v[188:191], v[176:179], v[52:55]
	v_mfma_f32_16x16x32_bf16 v[60:63], v[192:195], v[176:179], v[60:63]
	global_load_dwordx4 v[164:167], v[136:137], off offset:896
	global_load_dwordx4 v[168:171], v[138:139], off offset:896
	global_load_dwordx4 v[172:175], v[148:149], off offset:896
	global_load_dwordx4 v[176:179], v[150:151], off offset:896
	global_load_dwordx4 v[180:183], v[140:141], off offset:896
	global_load_dwordx4 v[184:187], v[142:143], off offset:896
	global_load_dwordx4 v[188:191], v[144:145], off offset:896
	global_load_dwordx4 v[192:195], v[146:147], off offset:896
	s_waitcnt vmcnt(24)
	v_mfma_f32_16x16x32_bf16 v[56:59], v[216:219], v[196:199], v[56:59]
	v_mfma_f32_16x16x32_bf16 v[44:47], v[220:223], v[196:199], v[44:47]
	v_mfma_f32_16x16x32_bf16 v[24:27], v[224:227], v[196:199], v[24:27]
	v_mfma_f32_16x16x32_bf16 v[16:19], v[228:231], v[196:199], v[16:19]
	v_mfma_f32_16x16x32_bf16 v[12:15], v[216:219], v[204:207], v[12:15]
	v_mfma_f32_16x16x32_bf16 v[8:11], v[220:223], v[204:207], v[8:11]
	v_mfma_f32_16x16x32_bf16 v[4:7], v[224:227], v[204:207], v[4:7]
	v_mfma_f32_16x16x32_bf16 v[0:3], v[228:231], v[204:207], v[0:3]
	v_mfma_f32_16x16x32_bf16 v[20:23], v[216:219], v[208:211], v[20:23]
	v_mfma_f32_16x16x32_bf16 v[28:31], v[220:223], v[208:211], v[28:31]
	v_mfma_f32_16x16x32_bf16 v[32:35], v[224:227], v[208:211], v[32:35]
	v_mfma_f32_16x16x32_bf16 v[36:39], v[228:231], v[208:211], v[36:39]
	v_mfma_f32_16x16x32_bf16 v[40:43], v[216:219], v[212:215], v[40:43]
	v_mfma_f32_16x16x32_bf16 v[48:51], v[220:223], v[212:215], v[48:51]
	v_mfma_f32_16x16x32_bf16 v[52:55], v[224:227], v[212:215], v[52:55]
	v_mfma_f32_16x16x32_bf16 v[60:63], v[228:231], v[212:215], v[60:63]
	global_load_dwordx4 v[196:199], v[136:137], off offset:960
	global_load_dwordx4 v[204:207], v[138:139], off offset:960
	global_load_dwordx4 v[208:211], v[148:149], off offset:960
	global_load_dwordx4 v[212:215], v[150:151], off offset:960
	global_load_dwordx4 v[216:219], v[140:141], off offset:960
	global_load_dwordx4 v[220:223], v[142:143], off offset:960
	global_load_dwordx4 v[224:227], v[144:145], off offset:960
	global_load_dwordx4 v[228:231], v[146:147], off offset:960
	s_waitcnt vmcnt(24)
	v_mfma_f32_16x16x32_bf16 v[56:59], v[100:103], v[84:87], v[56:59]
	v_mfma_f32_16x16x32_bf16 v[44:47], v[104:107], v[84:87], v[44:47]
	v_mfma_f32_16x16x32_bf16 v[24:27], v[108:111], v[84:87], v[24:27]
	v_mfma_f32_16x16x32_bf16 v[16:19], v[112:115], v[84:87], v[16:19]
	v_mfma_f32_16x16x32_bf16 v[12:15], v[100:103], v[88:91], v[12:15]
	v_mfma_f32_16x16x32_bf16 v[8:11], v[104:107], v[88:91], v[8:11]
	v_mfma_f32_16x16x32_bf16 v[4:7], v[108:111], v[88:91], v[4:7]
	v_mfma_f32_16x16x32_bf16 v[0:3], v[112:115], v[88:91], v[0:3]
	v_mfma_f32_16x16x32_bf16 v[20:23], v[100:103], v[92:95], v[20:23]
	v_mfma_f32_16x16x32_bf16 v[28:31], v[104:107], v[92:95], v[28:31]
	v_mfma_f32_16x16x32_bf16 v[32:35], v[108:111], v[92:95], v[32:35]
	v_mfma_f32_16x16x32_bf16 v[36:39], v[112:115], v[92:95], v[36:39]
	v_mfma_f32_16x16x32_bf16 v[40:43], v[100:103], v[96:99], v[40:43]
	v_mfma_f32_16x16x32_bf16 v[48:51], v[104:107], v[96:99], v[48:51]
	v_mfma_f32_16x16x32_bf16 v[52:55], v[108:111], v[96:99], v[52:55]
	v_mfma_f32_16x16x32_bf16 v[60:63], v[112:115], v[96:99], v[60:63]
	s_waitcnt vmcnt(16)
	v_mfma_f32_16x16x32_bf16 v[56:59], v[132:135], v[116:119], v[56:59]
	v_mfma_f32_16x16x32_bf16 v[44:47], v[152:155], v[116:119], v[44:47]
	v_mfma_f32_16x16x32_bf16 v[24:27], v[156:159], v[116:119], v[24:27]
	v_mfma_f32_16x16x32_bf16 v[16:19], v[160:163], v[116:119], v[16:19]
	v_mfma_f32_16x16x32_bf16 v[12:15], v[132:135], v[120:123], v[12:15]
	v_mfma_f32_16x16x32_bf16 v[8:11], v[152:155], v[120:123], v[8:11]
	v_mfma_f32_16x16x32_bf16 v[4:7], v[156:159], v[120:123], v[4:7]
	v_mfma_f32_16x16x32_bf16 v[0:3], v[160:163], v[120:123], v[0:3]
	v_mfma_f32_16x16x32_bf16 v[20:23], v[132:135], v[124:127], v[20:23]
	v_mfma_f32_16x16x32_bf16 v[28:31], v[152:155], v[124:127], v[28:31]
	v_mfma_f32_16x16x32_bf16 v[32:35], v[156:159], v[124:127], v[32:35]
	v_mfma_f32_16x16x32_bf16 v[36:39], v[160:163], v[124:127], v[36:39]
	v_mfma_f32_16x16x32_bf16 v[40:43], v[132:135], v[128:131], v[40:43]
	v_mfma_f32_16x16x32_bf16 v[48:51], v[152:155], v[128:131], v[48:51]
	v_mfma_f32_16x16x32_bf16 v[52:55], v[156:159], v[128:131], v[52:55]
	v_mfma_f32_16x16x32_bf16 v[60:63], v[160:163], v[128:131], v[60:63]
	s_waitcnt vmcnt(8)
; #define LAS __attribute__((address_space(3)))
; template <class Epi, bool PAIR>
; __device__ __forceinline__ void small_gemm(LAS unsigned char* lds, const bf16_t* A, int lda, const bf16_t* B, int ldb, int K, int nrg, int nct, size_t row_base, int col_base, const Epi& E, int G, int c) {
;     ...
;                 for (int ni = 0; ni < 4; ++ni) acc[mi][ni] = __builtin_amdgcn_mfma_f32_16x16x32_bf16(b[ni], a[mi], acc[mi][ni], 0, 0, 0);
;         }
;         __syncthreads();
; #pragma unroll
;         for (int mi = 0; mi < 4; ++mi)
; #pragma unroll
;             for (int ni = 0; ni < 4; ++ni) *(LAS f32x4*)(red + (wid * 64 + mi * 16 + fr) * 68 + ni * 16 + 4 * fq) = acc[mi][ni];
;         __syncthreads();
	v_mfma_f32_16x16x32_bf16 v[56:59], v[180:183], v[164:167], v[56:59]
	v_mfma_f32_16x16x32_bf16 v[44:47], v[184:187], v[164:167], v[44:47]
	v_mfma_f32_16x16x32_bf16 v[24:27], v[188:191], v[164:167], v[24:27]
	v_mfma_f32_16x16x32_bf16 v[16:19], v[192:195], v[164:167], v[16:19]
	v_mfma_f32_16x16x32_bf16 v[12:15], v[180:183], v[168:171], v[12:15]
	v_mfma_f32_16x16x32_bf16 v[8:11], v[184:187], v[168:171], v[8:11]
	v_mfma_f32_16x16x32_bf16 v[4:7], v[188:191], v[168:171], v[4:7]
	v_mfma_f32_16x16x32_bf16 v[0:3], v[192:195], v[168:171], v[0:3]
	v_mfma_f32_16x16x32_bf16 v[20:23], v[180:183], v[172:175], v[20:23]
	v_mfma_f32_16x16x32_bf16 v[28:31], v[184:187], v[172:175], v[28:31]
	v_mfma_f32_16x16x32_bf16 v[32:35], v[188:191], v[172:175], v[32:35]
	v_mfma_f32_16x16x32_bf16 v[36:39], v[192:195], v[172:175], v[36:39]
	v_mfma_f32_16x16x32_bf16 v[40:43], v[180:183], v[176:179], v[40:43]
	v_mfma_f32_16x16x32_bf16 v[48:51], v[184:187], v[176:179], v[48:51]
	v_mfma_f32_16x16x32_bf16 v[52:55], v[188:191], v[176:179], v[52:55]
	v_mfma_f32_16x16x32_bf16 v[60:63], v[192:195], v[176:179], v[60:63]
	s_waitcnt vmcnt(0)
	v_mfma_f32_16x16x32_bf16 v[56:59], v[216:219], v[196:199], v[56:59]
	v_mfma_f32_16x16x32_bf16 v[44:47], v[220:223], v[196:199], v[44:47]
	v_mfma_f32_16x16x32_bf16 v[24:27], v[224:227], v[196:199], v[24:27]
	v_mfma_f32_16x16x32_bf16 v[16:19], v[228:231], v[196:199], v[16:19]
	v_mfma_f32_16x16x32_bf16 v[12:15], v[216:219], v[204:207], v[12:15]
	v_mfma_f32_16x16x32_bf16 v[8:11], v[220:223], v[204:207], v[8:11]
	v_mfma_f32_16x16x32_bf16 v[4:7], v[224:227], v[204:207], v[4:7]
	v_mfma_f32_16x16x32_bf16 v[0:3], v[228:231], v[204:207], v[0:3]
	v_mfma_f32_16x16x32_bf16 v[20:23], v[216:219], v[208:211], v[20:23]
	v_mfma_f32_16x16x32_bf16 v[28:31], v[220:223], v[208:211], v[28:31]
	v_mfma_f32_16x16x32_bf16 v[32:35], v[224:227], v[208:211], v[32:35]
	v_mfma_f32_16x16x32_bf16 v[36:39], v[228:231], v[208:211], v[36:39]
	v_mfma_f32_16x16x32_bf16 v[40:43], v[216:219], v[212:215], v[40:43]
	v_mfma_f32_16x16x32_bf16 v[48:51], v[220:223], v[212:215], v[48:51]
	v_mfma_f32_16x16x32_bf16 v[52:55], v[224:227], v[212:215], v[52:55]
	v_mfma_f32_16x16x32_bf16 v[60:63], v[228:231], v[212:215], v[60:63]
	s_lshl_b32 s6, s14, 2
	s_sub_i32 s6, s2, s6
	v_lshl_add_u32 v92, s6, 6, v73
	v_ashrrev_i32_e32 v93, 31, v92
	s_barrier
	ds_write_b128 v64, v[56:59]
	ds_write_b128 v64, v[44:47] offset:64
	ds_write_b128 v64, v[24:27] offset:128
	ds_write_b128 v64, v[16:19] offset:192
	ds_write_b128 v64, v[12:15] offset:4352
	ds_write_b128 v64, v[8:11] offset:4416
	ds_write_b128 v64, v[4:7] offset:4480
	ds_write_b128 v64, v[0:3] offset:4544
	ds_write_b128 v64, v[20:23] offset:8704
	ds_write_b128 v64, v[28:31] offset:8768
	ds_write_b128 v64, v[32:35] offset:8832
	ds_write_b128 v64, v[36:39] offset:8896
	ds_write_b128 v64, v[40:43] offset:13056
	ds_write_b128 v64, v[48:51] offset:13120
	ds_write_b128 v64, v[52:55] offset:13184
	ds_write_b128 v64, v[60:63] offset:13248
	v_lshlrev_b64 v[0:1], 7, v[92:93]
	v_lshl_add_u64 v[32:33], s[90:91], 0, v[0:1]
	s_waitcnt lgkmcnt(0)
	s_barrier
; #define LAS __attribute__((address_space(3)))
;     __device__ __forceinline__ void piece(size_t row, int col, f32x4 v0, f32x4 v1, const f32x4 a0, const f32x4 a1, const f32x4 b0, const f32x4 b1, const f32x4 c0, const f32x4 c1,
;                                           float mean, float rstd, float& s, float& ss) const {
;         if constexpr (MODE == 1) { f32x4 r0, r1; unpack8(*(const u32x4*)(Tin + row * DM + col), r0, r1); v0 = r0 * ALPHA + v0; v1 = r1 * ALPHA + v1; }
;         if constexpr (MODE == 2) { v0 = ((v0 - a0 * mean) * rstd + b0) * scale; v1 = ((v1 - a1 * mean) * rstd + b1) * scale; }
;         if constexpr (RECOMP) { f32x4 r0, r1; unpack8(*(const u32x4*)(Tin + row * DM + col), r0, r1);
;             r0 = (r0 - mean) * rstd * a0 + b0; r1 = (r1 - mean) * rstd * a1 + b1; v0 = r0 * ALPHA + v0; v1 = r1 * ALPHA + v1;
;             if constexpr (MODE == 5) { v0 = v0 + c0; v1 = v1 + c1; } }
;         if constexpr (MODE == 4) { v0 = (v0 - a0 * mean) * rstd + b0; v1 = (v1 - a1 * mean) * rstd + b1;
; #pragma unroll
;             for (int e = 0; e < 4; ++e) { const float x = fmaxf(v0[e], 0.f), y = fmaxf(v1[e], 0.f); v0[e] = x * x; v1[e] = y * y; } }
;         if constexpr (PROD) {
; #pragma unroll
;             for (int e = 0; e < 4; ++e) { s += v0[e] + v1[e]; ss += v0[e] * v0[e] + v1[e] * v1[e]; } }
;         if constexpr (MODE == 5) { float* o = (float*)O + row * ldo + col; *(f32x4*)o = v0; *(f32x4*)(o + 4) = v1; }
;         else *(u32x4*)((bf16_t*)O + row * ldo + col) = pack8(v0, v1);
;     }
;     __device__ __forceinline__ static void stats_of(const f32x2* st, size_t row, int h, float& s, float& ss) {
;         const f32x4* sp = (const f32x4*)(st + row * 16 + h * 8); s = 0.f; ss = 0.f;
; #pragma unroll
; template <class Epi, bool PAIR>
; __device__ __forceinline__ void small_gemm(LAS unsigned char* lds, const bf16_t* A, int lda, const bf16_t* B, int ldb, int K, int nrg, int nct, size_t row_base, int col_base, const Epi& E, int G, int c) {
;     ...
;             const int r = tid >> 3, pc = tid & 7; f32x4 v0 = (f32x4){0.f, 0.f, 0.f, 0.f}, v1 = v0;
; #pragma unroll
;             for (int w = 0; w < 8; ++w) { v0 += *(const LAS f32x4*)(red + (w * 64 + r) * 68 + pc * 8); v1 += *(const LAS f32x4*)(red + (w * 64 + r) * 68 + pc * 8 + 4); }
;             E.small(row_base + rg * 64 + r, col_base + ct * 64 + pc * 8, v0, v1);
	global_load_dwordx4 v[0:3], v[32:33], off
	global_load_dwordx4 v[4:7], v[32:33], off offset:16
	global_load_dwordx4 v[8:11], v[32:33], off offset:32
	global_load_dwordx4 v[12:15], v[32:33], off offset:48
	global_load_dwordx4 v[16:19], v[32:33], off offset:64
	global_load_dwordx4 v[20:23], v[32:33], off offset:80
	global_load_dwordx4 v[24:27], v[32:33], off offset:96
	global_load_dwordx4 v[28:31], v[32:33], off offset:112
	ds_read_b128 v[32:35], v75
	ds_read_b128 v[36:39], v75 offset:16
	v_or_b32_e32 v44, s13, v74
	v_lshlrev_b64 v[40:41], 11, v[92:93]
	v_ashrrev_i32_e32 v45, 31, v44
	v_lshl_add_u64 v[40:41], s[88:89], 0, v[40:41]
	v_lshl_add_u64 v[40:41], v[44:45], 1, v[40:41]
	v_readlane_b32 s16, v254, 3
	global_load_dwordx4 v[40:43], v[40:41], off
	s_waitcnt lgkmcnt(1)
	v_pk_add_f32 v[60:61], v[34:35], 0 op_sel_hi:[1,0]
	v_pk_add_f32 v[68:69], v[32:33], 0 op_sel_hi:[1,0]
	s_waitcnt lgkmcnt(0)
	v_pk_add_f32 v[70:71], v[38:39], 0 op_sel_hi:[1,0]
	v_pk_add_f32 v[84:85], v[36:37], 0 op_sel_hi:[1,0]
	ds_read_b128 v[32:35], v75 offset:17408
	ds_read_b128 v[36:39], v75 offset:17424
	v_readlane_b32 s20, v254, 7
	v_readlane_b32 s21, v254, 8
	v_readlane_b32 s22, v254, 9
	v_readlane_b32 s23, v254, 10
	v_readlane_b32 s28, v254, 15
	v_readlane_b32 s29, v254, 16
	v_readlane_b32 s30, v254, 17
	v_readlane_b32 s31, v254, 18
	s_mov_b64 s[20:21], s[28:29]
	v_lshlrev_b64 v[94:95], 2, v[44:45]
	s_mov_b64 s[22:23], s[30:31]
	v_lshl_add_u64 v[52:53], s[20:21], 0, v[94:95]
	v_lshl_add_u64 v[62:63], s[22:23], 0, v[94:95]
	global_load_dwordx4 v[44:47], v[52:53], off offset:16
	global_load_dwordx4 v[48:51], v[52:53], off
	s_nop 0
	global_load_dwordx4 v[52:55], v[62:63], off offset:16
	global_load_dwordx4 v[56:59], v[62:63], off
	s_waitcnt lgkmcnt(1)
	v_pk_add_f32 v[86:87], v[60:61], v[34:35]
	ds_read_b128 v[60:63], v75 offset:34816
	v_pk_add_f32 v[68:69], v[68:69], v[32:33]
	ds_read_b128 v[32:35], v75 offset:34832
	s_waitcnt lgkmcnt(2)
	v_pk_add_f32 v[38:39], v[70:71], v[38:39]
	v_pk_add_f32 v[88:89], v[84:85], v[36:37]
	s_waitcnt lgkmcnt(1)
	v_pk_add_f32 v[90:91], v[86:87], v[62:63]
	v_pk_add_f32 v[96:97], v[68:69], v[60:61]
	s_waitcnt lgkmcnt(0)
	v_pk_add_f32 v[98:99], v[38:39], v[34:35]
	v_lshl_add_u64 v[38:39], s[50:51], 0, v[94:95]
	ds_read_b128 v[34:37], v75 offset:52224
	ds_read_b128 v[60:63], v75 offset:52240
	global_load_dwordx4 v[68:71], v[38:39], off offset:16
	global_load_dwordx4 v[84:87], v[38:39], off
	v_pk_add_f32 v[88:89], v[88:89], v[32:33]
	s_add_i32 s2, s2, s92
	s_waitcnt lgkmcnt(1)
	v_pk_add_f32 v[90:91], v[90:91], v[36:37]
	ds_read_b128 v[36:39], v76
	v_pk_add_f32 v[96:97], v[96:97], v[34:35]
	ds_read_b128 v[32:35], v77
	s_waitcnt lgkmcnt(2)
	v_pk_add_f32 v[98:99], v[98:99], v[62:63]
	v_pk_add_f32 v[88:89], v[88:89], v[60:61]
	ds_read_b128 v[60:63], v78
	s_waitcnt lgkmcnt(2)
	v_pk_add_f32 v[96:97], v[96:97], v[36:37]
	s_waitcnt lgkmcnt(1)
	v_pk_add_f32 v[98:99], v[98:99], v[34:35]
	ds_read_b128 v[34:37], v79
	v_pk_add_f32 v[38:39], v[90:91], v[38:39]
	v_pk_add_f32 v[32:33], v[88:89], v[32:33]
	ds_read_b128 v[88:91], v80
	s_waitcnt lgkmcnt(2)
	v_pk_add_f32 v[38:39], v[38:39], v[62:63]
	v_pk_add_f32 v[60:61], v[96:97], v[60:61]
	s_waitcnt lgkmcnt(1)
	v_pk_add_f32 v[96:97], v[98:99], v[36:37]
	v_pk_add_f32 v[98:99], v[32:33], v[34:35]
	ds_read_b128 v[32:35], v81
	s_waitcnt lgkmcnt(1)
	v_pk_add_f32 v[90:91], v[38:39], v[90:91]
	ds_read_b128 v[36:39], v82
	v_pk_add_f32 v[88:89], v[60:61], v[88:89]
	ds_read_b128 v[60:63], v83
	s_waitcnt lgkmcnt(2)
	v_pk_add_f32 v[32:33], v[98:99], v[32:33]
	v_pk_add_f32 v[34:35], v[96:97], v[34:35]
	s_waitcnt lgkmcnt(1)
	v_pk_add_f32 v[38:39], v[90:91], v[38:39]
	v_pk_add_f32 v[36:37], v[88:89], v[36:37]
	s_waitcnt lgkmcnt(0)
	v_pk_add_f32 v[32:33], v[32:33], v[60:61]
	v_pk_add_f32 v[34:35], v[34:35], v[62:63]
	s_cmp_gt_i32 s2, 63
	v_readlane_b32 s17, v254, 4
	s_waitcnt vmcnt(14)
	v_pk_add_f32 v[0:1], v[0:1], v[2:3]
	s_waitcnt vmcnt(13)
	v_pk_add_f32 v[2:3], v[4:5], v[6:7]
	v_pk_add_f32 v[0:1], v[0:1], 0 op_sel_hi:[1,0]
	v_readlane_b32 s18, v254, 5
	v_pk_add_f32 v[0:1], v[0:1], v[2:3]
	s_waitcnt vmcnt(12)
	v_pk_add_f32 v[2:3], v[8:9], v[10:11]
	s_waitcnt vmcnt(9)
	v_pk_add_f32 v[4:5], v[20:21], v[22:23]
	v_pk_add_f32 v[0:1], v[0:1], v[2:3]
	v_pk_add_f32 v[2:3], v[12:13], v[14:15]
	v_readlane_b32 s19, v254, 6
	v_pk_add_f32 v[0:1], v[0:1], v[2:3]
	v_pk_add_f32 v[2:3], v[16:17], v[18:19]
	v_readlane_b32 s24, v254, 11
	v_pk_add_f32 v[2:3], v[2:3], 0 op_sel_hi:[1,0]
	v_readlane_b32 s25, v254, 12
	v_pk_add_f32 v[2:3], v[2:3], v[4:5]
	s_waitcnt vmcnt(8)
	v_pk_add_f32 v[4:5], v[24:25], v[26:27]
	s_waitcnt vmcnt(6)
	v_lshlrev_b32_e32 v10, 16, v42
	v_pk_add_f32 v[2:3], v[2:3], v[4:5]
	v_pk_add_f32 v[4:5], v[28:29], v[30:31]
	v_and_b32_e32 v11, 0xffff0000, v42
	v_pk_add_f32 v[2:3], v[2:3], v[4:5]
	v_lshlrev_b32_e32 v4, 16, v41
	v_pk_add_f32 v[0:1], v[0:1], v[2:3]
	v_and_b32_e32 v3, 0xffff0000, v40
	v_pk_mul_f32 v[0:1], v[0:1], s[0:1] op_sel_hi:[1,0]
	v_and_b32_e32 v5, 0xffff0000, v41
	v_fma_f32 v1, -v0, v0, v1
	v_max_f32_e32 v1, 0, v1
	v_add_f32_e32 v1, 0x3727c5ac, v1
	v_rsq_f32_e32 v2, v1
	v_lshlrev_b32_e32 v1, 16, v40
	v_lshlrev_b32_e32 v8, 16, v43
	v_and_b32_e32 v9, 0xffff0000, v43
	v_sub_f32_e32 v5, v5, v0
	v_sub_f32_e32 v4, v4, v0
	v_sub_f32_e32 v7, v3, v0
	v_sub_f32_e32 v6, v1, v0
	v_sub_f32_e32 v9, v9, v0
	v_sub_f32_e32 v8, v8, v0
	v_sub_f32_e32 v1, v11, v0
	v_sub_f32_e32 v0, v10, v0
	v_pk_mul_f32 v[4:5], v[2:3], v[4:5] op_sel_hi:[0,1]
	v_pk_mul_f32 v[0:1], v[2:3], v[0:1] op_sel_hi:[0,1]
	v_pk_mul_f32 v[6:7], v[2:3], v[6:7] op_sel_hi:[0,1]
	s_waitcnt vmcnt(2)
	v_pk_fma_f32 v[4:5], v[50:51], v[4:5], v[58:59]
	v_pk_mul_f32 v[2:3], v[2:3], v[8:9] op_sel_hi:[0,1]
	v_pk_fma_f32 v[0:1], v[44:45], v[0:1], v[52:53]
	v_pk_fma_f32 v[2:3], v[46:47], v[2:3], v[54:55]
	v_pk_fma_f32 v[4:5], v[4:5], s[4:5], v[38:39] op_sel_hi:[1,0,1]
	v_pk_fma_f32 v[8:9], v[0:1], s[4:5], v[32:33] op_sel_hi:[1,0,1]
	v_pk_fma_f32 v[6:7], v[48:49], v[6:7], v[56:57]
	v_pk_fma_f32 v[10:11], v[2:3], s[4:5], v[34:35] op_sel_hi:[1,0,1]
	s_waitcnt vmcnt(0)
	v_pk_add_f32 v[2:3], v[86:87], v[4:5]
	v_pk_add_f32 v[4:5], v[68:69], v[8:9]
	v_lshlrev_b64 v[8:9], 12, v[92:93]
	v_pk_fma_f32 v[6:7], v[6:7], s[4:5], v[36:37] op_sel_hi:[1,0,1]
	v_lshl_add_u64 v[8:9], s[56:57], 0, v[8:9]
	v_pk_add_f32 v[0:1], v[84:85], v[6:7]
	v_pk_add_f32 v[6:7], v[70:71], v[10:11]
	v_lshl_add_u64 v[8:9], v[8:9], 0, v[94:95]
	v_readlane_b32 s26, v254, 13
	v_readlane_b32 s27, v254, 14
	global_store_dwordx4 v[8:9], v[0:3], off
	global_store_dwordx4 v[8:9], v[4:7], off offset:16
	s_cbranch_scc0 .LBB0_1486
